# SEL/WIN first K/V tile loads issued before the Q-load wait
# speedup vs baseline: 1.0481x; 1.0021x over previous
; DI float bflo(unsigned w) { return __uint_as_float(w << 16); }
; DI float bfhi(unsigned w) { return __uint_as_float(w & 0xffff0000u); }
; #define GATES WSP(float, WS_GATES)
; #define MASKS WSP(unsigned, WS_MASK)
; #define lds fresh_lds(lds0)
; template <int DQK, int MODE> ...
;     ...
;     FL_GLOAD(t0);
;     __syncthreads();
;     FL_LSTORE(0);
;     if (t0 + 1 < t1) FL_GLOAD(t0 + 1);
;     __syncthreads();
; __global__ void __launch_bounds__(512) mega_fwd(Params P) {
;     ...
;                 const int qb = 31 - it / 24, r24 = it % 24, bh = r24 % 12, b = bh / 6, h = bh % 6, g = h / 3, q0 = qb * 256;
;                 const size_t rb = (size_t)b * SEQ; const size_t qrow = rb + q0 + 32 * wid + r32;
;                 if (r24 < 12) {
;                     f32x16 tot[2]; tot[0] = (f32x16){}; tot[1] = (f32x16){};
;                     flash_unit<96, MODE_CAUSAL>(lds, wv0, QMLA + (rb + q0) * 576 + h * 96, 576, KVB + rb * 768 + h * 64, 768, PROJ + rb * NPROJ + PC_KR, NPROJ,
;                                                 KVB + rb * 768 + 384 + h * 64, 768, q0, 0, (q0 + 256) / 64, 0.10206207261596577f * LOG2E, (u32x4){}, 1.f, tot, nullptr, WSP(float, WS_ROPE));
;                     store_o(tot, HN + qrow * DM + h * 64, hi);
;                 } else {
;                     const float g1 = GATES[qrow * 32 + h * 3 + 1], g2 = GATES[qrow * 32 + h * 3 + 2];
;                     const u32x4 mw = *(const u32x4*)(MASKS + ((size_t)(b * 2 + g) * SEQ + q0 + 32 * wid + r32) * 4);
;                     f32x16 tot[2];
;                     { const bf16_t* oc = OCMP + qrow * 384 + h * 64;
; #pragma unroll
;                       for (int d0 = 0; d0 < 2; ++d0)
; #pragma unroll
;                           for (int j = 0; j < 4; ++j) { const u32x2 w = *(const u32x2*)(oc + 32 * d0 + 8 * j + 4 * hi); tot[d0][4 * j] = bflo(w.x); tot[d0][4 * j + 1] = bfhi(w.x); tot[d0][4 * j + 2] = bflo(w.y); tot[d0][4 * j + 3] = bfhi(w.y); } }
;                     const bf16_t* Qp = PROJ + (rb + q0) * NPROJ + PC_NQ + 64 * h;
;                     flash_unit<64, MODE_SEL>(lds, wv0, Qp, NPROJ, PROJ + rb * NPROJ + PC_KS + 64 * g, NPROJ, nullptr, 0, PROJ + rb * NPROJ + PC_VS + 64 * g, NPROJ,
;                                              q0, 0, (q0 + 256) / 64, 0.125f * LOG2E, mw, g1, tot, nullptr);
.LBB0_1306:
	s_or_b64 exec, exec, s[0:1]
	v_mov_b32_e32 v0, s38
	s_waitcnt lgkmcnt(0)
	s_barrier
	ds_read_b32 v0, v0
	s_movk_i32 s0, 0x3ff
	s_waitcnt lgkmcnt(0)
	v_cmp_lt_i32_e32 vcc, s0, v0
	v_readfirstlane_b32 s34, v0
	s_mov_b64 s[0:1], -1
	s_cbranch_vccnz .LBB0_1303
	s_cmpk_lt_i32 s34, 0x300
	s_cbranch_scc0 .LBB0_1372
	s_mul_hi_i32 s0, s34, 0xd5555555
	s_lshr_b32 s1, s0, 31
	s_lshr_b32 s0, s0, 2
	s_add_i32 s4, s0, s1
	s_mul_hi_i32 s0, s34, 0x2aaaaaab
	s_lshr_b32 s1, s0, 31
	s_lshr_b32 s0, s0, 2
	s_add_i32 s0, s0, s1
	s_mul_i32 s0, s0, 24
	s_sub_i32 s6, s34, s0
	s_mul_i32 s0, s6, 43
	s_sext_i32_i16 s1, s0
	s_lshr_b32 s1, s1, 9
	s_bfe_u32 s0, s0, 0x1000f
	s_add_i32 s0, s1, s0
	s_mul_i32 s0, s0, 12
	s_sub_i32 s1, s6, s0
	s_bfe_i32 s0, s1, 0x80000
	s_mul_i32 s0, s0, 43
	s_bfe_u32 s5, s0, 0x1000f
	s_bfe_u32 s0, s0, 0x80008
	s_add_i32 s0, s0, s5
	s_mul_i32 s5, s0, 6
	s_sub_i32 s1, s1, s5
	s_lshl_b32 s35, s4, 8
	s_bfe_i64 s[8:9], s[0:1], 0x80000
	s_add_i32 s36, s35, 0x1f00
	s_lshl_b64 s[4:5], s[8:9], 13
	s_add_u32 s26, s4, s36
	s_addc_u32 s27, s5, 0
	s_sext_i32_i8 s37, s1
	v_lshl_add_u64 v[180:181], s[26:27], 0, v[174:175]
	s_mov_b64 s[4:5], -1
	s_cmp_gt_i32 s6, 11
	s_mul_hi_i32 s45, s8, 0x2800000
	s_mul_i32 s46, s8, 0x2800000
	s_cbranch_scc0 .LBB0_1346
	s_bfe_i32 s1, s1, 0x80000
	s_mulk_i32 s1, 0x56
	s_bfe_u32 s4, s1, 0x1000f
	s_bfe_u32 s1, s1, 0x80008
	s_add_i32 s1, s1, s4
	s_sext_i32_i8 s6, s1
	s_sext_i32_i8 s0, s0
	s_lshl_b32 s0, s0, 14
	s_lshl_b32 s1, s6, 13
	s_add_i32 s1, s1, s0
	s_add_u32 s0, s1, s36
	s_addc_u32 s1, 0, 0
	v_mov_b64_e32 v[6:7], s[18:19]
	v_lshl_add_u64 v[4:5], s[0:1], 0, v[174:175]
	v_mad_u64_u32 v[6:7], s[0:1], v180, s72, v[6:7]
	v_mov_b32_e32 v0, v7
	v_lshlrev_b64 v[2:3], 7, v[180:181]
	v_mad_u64_u32 v[8:9], s[0:1], v181, s72, v[0:1]
	s_mul_i32 s80, s37, 3
	v_lshl_add_u64 v[2:3], s[14:15], 0, v[2:3]
	s_mul_i32 s0, s27, 0x1400
	s_mul_hi_u32 s1, s26, 0x1400
	v_lshl_add_u64 v[2:3], s[80:81], 2, v[2:3]
	s_lshl_b32 s9, s37, 6
	s_lshl_b32 s80, s37, 7
	s_add_i32 s1, s1, s0
	s_mul_i32 s0, s26, 0x1400
	s_add_u32 s0, s39, s0
	v_mov_b32_e32 v7, v8
	s_addc_u32 s1, s40, s1
	v_lshl_add_u64 v[6:7], v[6:7], 0, s[80:81]
	v_mov_b32_e32 v179, v1
	s_add_u32 s30, s0, s80
	v_lshl_add_u64 v[4:5], v[4:5], 4, s[16:17]
	v_lshl_add_u64 v[6:7], v[6:7], 0, v[178:179]
	s_addc_u32 s31, s1, 0
	s_mov_b32 s1, s81
	v_mov_b32_e32 v0, v1
	flat_load_dwordx2 v[182:183], v[2:3] offset:4
	s_nop 0
	flat_load_dwordx4 v[2:5], v[4:5]
	s_nop 0
	flat_load_dwordx2 v[198:199], v[6:7]
	flat_load_dwordx2 v[196:197], v[6:7] offset:16
	flat_load_dwordx2 v[194:195], v[6:7] offset:32
	flat_load_dwordx2 v[192:193], v[6:7] offset:48
	flat_load_dwordx2 v[190:191], v[6:7] offset:64
	flat_load_dwordx2 v[188:189], v[6:7] offset:80
	flat_load_dwordx2 v[186:187], v[6:7] offset:96
	flat_load_dwordx2 v[184:185], v[6:7] offset:112
	v_readlane_b32 s7, v254, 6
	v_mbcnt_lo_u32_b32 v0, -1, v0
	v_mbcnt_hi_u32_b32 v26, -1, v0
	v_and_b32_e32 v27, 31, v26
	v_bfe_u32 v28, v26, 5, 1
	v_or_b32_e32 v0, s7, v27
	v_mov_b64_e32 v[6:7], s[30:31]
	v_mad_i64_i32 v[6:7], s[4:5], v0, s69, v[6:7]
	v_lshlrev_b32_e32 v0, 4, v28
	v_lshl_add_u64 v[6:7], v[6:7], 0, v[0:1]
	s_waitcnt vmcnt(0)
	flat_load_dwordx4 v[84:87], v[6:7] offset:832
	flat_load_dwordx4 v[80:83], v[6:7] offset:864
	flat_load_dwordx4 v[10:13], v[6:7] offset:896
	s_nop 0
	flat_load_dwordx4 v[6:9], v[6:7] offset:928
	s_add_u32 s0, s39, s46
	v_or_b32_e32 v14, s79, v26
	s_addc_u32 s4, s40, s45
	s_lshl_b32 s5, s6, 7
	v_and_b32_e32 v15, 7, v26
	v_ashrrev_i32_e32 v24, 3, v14
	s_add_u32 s28, s0, s5
	v_lshlrev_b32_e32 v29, 4, v15
	v_mul_lo_u32 v14, v24, s69
	v_mov_b32_e32 v23, v1
	s_addc_u32 s29, s4, 0
	v_or_b32_e32 v22, v29, v14
	v_lshl_add_u64 v[18:19], s[28:29], 0, v[22:23]
	s_movk_i32 s4, 0x90
	v_mul_lo_u32 v23, v24, s4
	v_mov_b32_e32 v25, v1
	v_add3_u32 v129, s1, v23, v29
	v_add_u32_e32 v24, 0x50000, v22
	v_lshl_add_u64 v[24:25], s[28:29], 0, v[24:25]
	v_add_u32_e32 v226, 0xa0000, v22
	v_mov_b32_e32 v227, v1
	v_lshl_add_u64 v[226:227], s[28:29], 0, v[226:227]
	v_add_u32_e32 v232, 0xf0000, v22
	v_mov_b32_e32 v233, v1
	v_lshl_add_u64 v[232:233], s[28:29], 0, v[232:233]
	v_mad_u32_u24 v131, v27, s4, v0
	v_lshlrev_b32_e32 v128, 2, v28
	v_lshrrev_b32_e32 v0, 2, v26
	s_add_i32 s0, s35, 0x2000
	s_add_i32 s48, s36, s7
	v_and_or_b32 v0, v0, 3, v128
	v_mov_b32_e32 v30, v1
	v_mov_b32_e32 v31, v1
	s_lshr_b32 s47, s0, 6
	v_mov_b32_e32 v23, v1
	v_mov_b32_e32 v28, v1
	v_mov_b32_e32 v29, v1
	s_mov_b32 s53, s81
	s_mov_b32 s50, 0
	s_or_b32 s49, s48, 31
	s_add_i32 s0, s47, -1
	v_mov_b32_e32 v179, 0
	s_mov_b32 s51, 63
	global_load_dwordx4 v[14:17], v[18:19], off offset:2112
	s_nop 0
	global_load_dwordx4 v[18:21], v[18:19], off offset:2368
	global_load_dwordx4 v[88:91], v[24:25], off offset:2368
	global_load_dwordx4 v[92:95], v[24:25], off offset:2112
	s_waitcnt vmcnt(0) lgkmcnt(0)
	s_waitcnt lgkmcnt(0)
	s_barrier
	s_waitcnt vmcnt(0)
	ds_write_b128 v129, v[14:17]
	ds_write_b128 v129, v[18:21] offset:36864
	v_add_u32_e32 v229, 0x2400, v129
	ds_write_b128 v229, v[92:95]
	ds_write_b128 v229, v[88:91] offset:36864
	global_load_dwordx4 v[88:91], v[226:227], off offset:2368
	global_load_dwordx4 v[92:95], v[226:227], off offset:2112
	global_load_dwordx4 v[222:225], v[232:233], off offset:2368
	global_load_dwordx4 v[218:221], v[232:233], off offset:2112
	v_lshlrev_b32_e32 v14, 1, v26
	v_and_b32_e32 v14, 32, v14
	v_lshlrev_b32_e32 v16, 3, v26
	v_and_or_b32 v14, v16, 24, v14
	v_or_b32_e32 v15, s48, v27
	v_mad_u32_u24 v130, v0, s4, v14
	v_add_u32_e32 v0, 0xf0000, v22
	v_mov_b32_e32 v16, v1
	v_mov_b32_e32 v17, v1
	v_mov_b32_e32 v18, v1
	v_mov_b32_e32 v19, v1
	v_mov_b32_e32 v20, v1
	v_mov_b32_e32 v21, v1
	v_mov_b32_e32 v22, v1
	v_mov_b32_e32 v24, v1
	v_mov_b32_e32 v25, v1
	v_mov_b32_e32 v26, v1
	v_mov_b32_e32 v27, v1
	v_mov_b64_e32 v[46:47], v[30:31]
	v_mov_b32_e32 v14, 0xf149f2ca
	v_mov_b64_e32 v[44:45], v[28:29]
	v_mov_b64_e32 v[42:43], v[26:27]
	v_mov_b64_e32 v[40:41], v[24:25]
	v_mov_b64_e32 v[38:39], v[22:23]
	v_mov_b64_e32 v[36:37], v[20:21]
	v_mov_b64_e32 v[34:35], v[18:19]
	v_mov_b64_e32 v[32:33], v[16:17]
	s_waitcnt lgkmcnt(0)
	s_barrier
	s_branch .LBB0_1311

; #define FL_LSTORE(buf) do { *(LAS u32x4*)(lds + AT_K + (buf) * KBUF + srow * KP2 + sch * 16) = rk1; \
;         if (DQK == 96 && tid < 256) *(LAS u32x4*)(lds + AT_K + (buf) * KBUF + srow2 * KP2 + 128 + sch2 * 16) = rk2; \
;         *(LAS u32x4*)(lds + AT_V + (buf) * VBUF + srow * VP2 + sch * 16) = rv; } while (0)
; #define lds fresh_lds(lds0)
; template <int DQK, int MODE> ...
;     ...
;     FL_GLOAD(t0);
;     __syncthreads();
;     FL_LSTORE(0);
;     if (t0 + 1 < t1) FL_GLOAD(t0 + 1);
;     __syncthreads();
; __global__ void __launch_bounds__(512) mega_fwd(Params P) {
;     ...
;                     const int tw0 = (q0 >= 512) ? (q0 - 512) / 64 : 0;
;                     flash_unit<64, MODE_WIN>(lds, wv0, Qp, NPROJ, PROJ + rb * NPROJ + PC_KW + 64 * g, NPROJ, nullptr, 0, PROJ + rb * NPROJ + PC_VW + 64 * g, NPROJ,
;                                              q0, tw0, (q0 + 256) / 64, 0.125f * LOG2E, (u32x4){}, g2, tot, nullptr);
.LBB0_1329:
	s_mov_b32 s6, s53
	v_mov_b32_e32 v0, v1
	s_barrier
	v_readlane_b32 s0, v254, 6
	v_mbcnt_lo_u32_b32 v0, -1, v0
	v_mbcnt_hi_u32_b32 v48, -1, v0
	v_and_b32_e32 v50, 31, v48
	v_bfe_u32 v49, v48, 5, 1
	v_or_b32_e32 v0, s0, v50
	v_mov_b64_e32 v[2:3], s[30:31]
	v_mad_i64_i32 v[2:3], s[0:1], v0, s69, v[2:3]
	v_lshlrev_b32_e32 v0, 4, v49
	v_lshl_add_u64 v[14:15], v[2:3], 0, v[0:1]
	flat_load_dwordx4 v[2:5], v[14:15] offset:832
	flat_load_dwordx4 v[6:9], v[14:15] offset:864
	flat_load_dwordx4 v[10:13], v[14:15] offset:896
	flat_load_dwordx4 v[112:115], v[14:15] offset:928
	s_add_i32 s0, s35, 0x1d00
	s_lshr_b32 s0, s0, 6
	s_cmpk_gt_i32 s36, 0x1ff
	s_cselect_b32 s7, s0, 0
	v_or_b32_e32 v0, s79, v48
	s_lshl_b32 s0, s7, 6
	v_ashrrev_i32_e32 v51, 3, v0
	v_and_b32_e32 v53, 7, v48
	v_add_u32_e32 v0, s0, v51
	v_lshlrev_b32_e32 v52, 3, v53
	v_mul_lo_u32 v0, v0, s76
	v_or_b32_e32 v0, v0, v52
	v_lshlrev_b32_e32 v0, 1, v0
	v_lshl_add_u64 v[14:15], s[28:29], 0, v[0:1]
	s_movk_i32 s4, 0x90
	v_mov_b32_e32 v210, v179
	s_or_b32 s1, s7, 1
	v_lshlrev_b32_e32 v0, 4, v53
	v_permlane32_swap_b32_e32 v179, v210
	s_cmp_lt_u32 s1, s47
	flat_load_dwordx4 v[116:119], v[14:15] offset:2624
	flat_load_dwordx4 v[120:123], v[14:15] offset:2880
	s_waitcnt vmcnt(0) lgkmcnt(0)
	v_mul_lo_u32 v14, v51, s4
	v_add3_u32 v14, s6, v14, v0
	s_waitcnt lgkmcnt(0)
	s_barrier
	s_waitcnt vmcnt(0)
	ds_write_b128 v14, v[116:119]
	ds_write_b128 v14, v[120:123] offset:28672
	s_cbranch_scc0 .LBB0_1331
	v_lshl_add_u32 v0, s1, 6, v51
	v_mul_lo_u32 v0, v0, s76
	v_or_b32_e32 v0, v0, v52
	v_lshlrev_b32_e32 v0, 1, v0
	v_lshl_add_u64 v[54:55], s[28:29], 0, v[0:1]
	flat_load_dwordx4 v[116:119], v[54:55] offset:2624
	flat_load_dwordx4 v[120:123], v[54:55] offset:2880
